# k57 + one static s_setprio 1 for waves 4-7 for the duration of the prompt attention phase (reset to 0 at the conv phase entry)
# baseline (speedup 1.0000x reference)
.LBB0_457:
	s_cmp_lt_u32 s93, 4
	s_cbranch_scc1 .Lattprio_skip
	s_setprio 1

.LBB0_498:
	s_setprio 0
	v_mbcnt_lo_u32_b32 v0, -1, 0
	v_mbcnt_hi_u32_b32 v0, -1, v0
	s_mov_b64 s[14:15], s[96:97]
	v_add_u32_e32 v6, s73, v0
	s_load_dwordx4 s[16:19], s[14:15], 0xd8
	s_load_dwordx2 s[40:41], s[14:15], 0x20
	s_load_dwordx8 s[4:11], s[14:15], 0x78
	s_and_b32 s98, s92, 14
	s_xor_b32 s98, s98, 0
	s_or_b32 s98, s98, s93
	s_cmp_eq_u32 s98, 0
	s_cbranch_scc0 .Lsconv_pf_done
	s_waitcnt lgkmcnt(0)
	s_lshr_b32 s98, s92, 4
	s_lshl_b32 s98, s98, 1
	s_and_b32 s99, s92, 1
	s_or_b32 s98, s98, s99
	s_mul_i32 s98, s98, 0xf000
	s_add_u32 s98, s40, s98
	s_addc_u32 s99, s41, 0
	v_lshlrev_b32_e32 v249, 7, v0
	global_load_dword v252, v249, s[98:99]
	s_add_u32 s98, s98, 0x2000
	s_addc_u32 s99, s99, 0
	global_load_dword v252, v249, s[98:99]
	s_add_u32 s98, s98, 0x2000
	s_addc_u32 s99, s99, 0
	global_load_dword v252, v249, s[98:99]
	s_add_u32 s98, s98, 0x2000
	s_addc_u32 s99, s99, 0
	global_load_dword v252, v249, s[98:99]
	s_add_u32 s98, s98, 0x2000
	s_addc_u32 s99, s99, 0
	global_load_dword v252, v249, s[98:99]
	s_add_u32 s98, s98, 0x2000
	s_addc_u32 s99, s99, 0
	global_load_dword v252, v249, s[98:99]
	s_add_u32 s98, s98, 0x2000
	s_addc_u32 s99, s99, 0
	global_load_dword v252, v249, s[98:99]
